# v35: v33 + static priority raise for waves 4-7 during the P11 gated-conv epilogue
# speedup vs baseline: 1.0017x; 1.0017x over previous
; #define PG8_WAIT_V(n) asm volatile("s_waitcnt vmcnt(" #n ")" ::: "memory")
; #define PG8_BAR __builtin_amdgcn_s_barrier()
; template <class Epi, class Sched>
; __device__ __forceinline__ void gemm_phase(LAS unsigned char* lds, const Gemm g, const Sched& S, const Epi& E) {
;     ...
;     PG8_WAIT_V(0);
;     PG8_BAR;
; __device__ __forceinline__ void xcd_barrier(const XcdBarrier& b) {
;     asm volatile("s_waitcnt vmcnt(0)" ::: "memory");
;     __syncthreads();
;     if (threadIdx.x == 0) {
;         unsigned* bar = b.bar;
;         __builtin_amdgcn_s_waitcnt(0);
;         unsigned nloc = b.st[0], nx = b.st[1];
;         if (nloc == 0u) { xcd_barrier_complete(bar, b.x, nloc, nx); b.st[0] = nloc; b.st[1] = nx; }
.LBB0_806:
	s_waitcnt vmcnt(0)
	v_readlane_b32 s82, v254, 2
	s_mov_b64 s[84:85], s[42:43]
	v_readlane_b32 s86, v254, 6
	v_readlane_b32 s42, v254, 4
	v_readlane_b32 s83, v254, 3
	v_readlane_b32 s87, v254, 7
	v_readlane_b32 s43, v254, 5
	s_barrier
.LBB0_807:
	s_setprio 0
	s_and_b64 vcc, exec, s[42:43]
	s_cbranch_vccz .LBB0_820
	s_mov_b64 s[4:5], 0
	s_cmp_lg_u32 s26, 0
	s_mov_b64 s[6:7], 0
	s_cbranch_scc0 .LBB0_821
	s_waitcnt vmcnt(0)
	s_waitcnt vmcnt(0) lgkmcnt(0)
	s_barrier
	s_and_saveexec_b64 s[6:7], s[86:87]
	s_cbranch_execz .LBB0_1474
	s_add_i32 s8, 0, 0x23ff0
	v_mov_b32_e32 v0, s8
	s_waitcnt vmcnt(0) expcnt(0) lgkmcnt(0)
	ds_read_b32 v2, v0
	s_add_i32 s8, 0, 0x23ff4
	v_mov_b32_e32 v0, s8
	ds_read_b32 v0, v0
	s_waitcnt lgkmcnt(1)
	v_cmp_ne_u32_e32 vcc, 0, v2
	s_cbranch_vccnz .LBB0_1080
	s_load_dwordx2 s[12:13], s[82:83], 0x4
	s_add_u32 s8, s36, 0x2f000200
	s_addc_u32 s9, s37, 0
	s_add_u32 s10, s36, 0x2f000400
	s_addc_u32 s11, s37, 0
	s_waitcnt lgkmcnt(0)
	s_mul_i32 s27, s12, s3
	s_add_u32 s12, s36, 0x2f000500
	s_mul_i32 s27, s27, s13
	s_addc_u32 s13, s37, 0
	s_add_u32 s14, s36, 0x2f000600
	s_addc_u32 s15, s37, 0
	s_add_u32 s18, s36, 0x2f000700
	s_addc_u32 s19, s37, 0
	s_add_u32 s20, s36, 0x2f000800
	s_addc_u32 s21, s37, 0
	s_add_u32 s22, s36, 0x2f000900
	s_addc_u32 s23, s37, 0
	s_add_u32 s28, s36, 0x2f000a00
	s_addc_u32 s29, s37, 0
	s_add_u32 s30, s36, 0x2f000b00
	s_addc_u32 s31, s37, 0
	s_add_u32 s44, s36, 0x2f000c00
	s_addc_u32 s45, s37, 0
	s_add_u32 s46, s36, 0x2f000d00
	s_addc_u32 s47, s37, 0
	s_add_u32 s48, s36, 0x2f000e00
	s_addc_u32 s49, s37, 0
	s_add_u32 s50, s36, 0x2f000f00
	s_addc_u32 s51, s37, 0
	s_add_u32 s52, s36, 0x2f001000
	s_addc_u32 s53, s37, 0
	s_add_u32 s54, s36, 0x2f001100
	s_addc_u32 s55, s37, 0
	s_add_u32 s56, s36, 0x2f001200
	s_addc_u32 s57, s37, 0
	s_add_u32 s58, s36, 0x2f001300
	s_addc_u32 s59, s37, 0
	s_mov_b32 s33, 1
	v_mov_b32_e32 v16, 0
	s_branch .LBB0_813
